# w2 + first two V transpose-read groups hoisted to the head of each attention step (LDS reads in flight under the DMA/SALU block)
# baseline (speedup 1.0000x reference)
; #define LAS __attribute__((address_space(3)))
; #define AT_TR4(slot, d) do { const unsigned _a = vaddr + (unsigned)vo[d]; AT_TR(r[slot][0], _a, 0); AT_TR(r[slot][1], _a, 16 * 256); AT_TR(r[slot][2], _a, 32 * 256); AT_TR(r[slot][3], _a, 48 * 256); } while (0)
; #define AT_TR4(slot, d) do { const unsigned _a = vaddr + (unsigned)vo[d]; AT_TR(r[slot][0], _a, 0); AT_TR(r[slot][1], _a, 16 * 256); AT_TR(r[slot][2], _a, 32 * 256); AT_TR(r[slot][3], _a, 48 * 256); } while (0)
; #define AT_STAGE(gbase, so, i, ldsoff) do { const int _ii = (i) < NT ? (i) : NT - 1; const size_t _go = (size_t)((tstart + _ii) & tmask) * (64 * 1024); _Pragma("unroll") for (int _i = 0; _i < 2; ++_i) \
;         __builtin_amdgcn_global_load_lds((const unsigned*)((gbase) + _go + (so)[_i]), (LAS unsigned*)(lds + (ldsoff) + (2 * w + _i) * 1024), 16, 0, 0); } while (0)
; template <bool QK, bool PV> ...
;     bf16x8 pn[2][2];
;     s16x4 r[3][4];
;     ...
;     if constexpr (PV) { AT_TR4(0, 0); AT_TR4(1, 1);
;         const bf16x8 ones = (bf16x8){0x3f80, 0x3f80, 0x3f80, 0x3f80, 0x3f80, 0x3f80, 0x3f80, 0x3f80};
; #pragma unroll
;         for (int c = 0; c < 2; ++c)
; #pragma unroll
;             for (int si = 0; si < 2; ++si) ol[c] = __builtin_amdgcn_mfma_f32_16x16x32_bf16(ones, pf[c][si], ol[c], 0, 0, 0); }
; __device__ __forceinline__ void attn_unit(LAS unsigned char* lds, int seq, int h, int qb, bf16_t* UQ, const bf16_t* KB, const bf16_t* VB, const float* rel_bias, const float* subln, float lam, float bmax) {
;     ...
;     for (int i = 1; i < NT - 1; ++i) {
;         AT_STAGE(kg, kso, i + 3, k_i); AT_STAGE(vg, vso, i + 2, AT_V0 + ((i + 2) & 3) * AT_TILE);
;         AT_TB((tstart + i + 1) & tmask);
;         attn_step<true, true>(lds + k_n, lds0 + AT_V0 + ((i - 1) & 3) * AT_TILE, kfo, vo, qf, s, pf, o, ol, tbv);
.Lat_xskip_s:
.LBB0_514:
	s_and_b32 s99, s55, 0xc000
	s_add_i32 s99, s99, 0xc000
	v_add_u32_e32 v228, s99, v186
	ds_read_b64_tr_b16 v[220:221], v228 offset:0
	ds_read_b64_tr_b16 v[222:223], v228 offset:0x1000
	ds_read_b64_tr_b16 v[224:225], v228 offset:0x2000
	ds_read_b64_tr_b16 v[226:227], v228 offset:0x3000
	v_add_u32_e32 v236, s99, v187
	ds_read_b64_tr_b16 v[228:229], v236 offset:0
	ds_read_b64_tr_b16 v[230:231], v236 offset:0x1000
	ds_read_b64_tr_b16 v[232:233], v236 offset:0x2000
	ds_read_b64_tr_b16 v[234:235], v236 offset:0x3000
	s_mov_b32 s61, s58
	s_add_i32 s3, s60, 3
	s_min_u32 s3, s3, s45
	s_add_i32 s3, s3, s46
	s_and_b32 s3, s3, s45
	s_lshl_b32 s3, s3, 16
	s_add_u32 s22, s20, s3
	s_addc_u32 s23, s50, 0
	s_add_i32 s3, s55, 0xffffc000
	s_and_b32 s3, s3, 0xc000
	s_add_i32 s3, s49, s3
	s_add_i32 m0, s3, 0xc000
	s_nop 0
	global_load_lds_dwordx4 v164, s[22:23]
	s_add_i32 m0, s3, 0xc400
	s_mov_b32 s58, s2
	global_load_lds_dwordx4 v168, s[22:23]
	s_add_i32 s2, s52, s60
	s_and_b32 s62, s2, s45
	s_lshl_b32 s2, s62, 6
	s_sub_i32 s3, s2, s51
	s_cmp_lt_i32 s2, s53
	s_cselect_b64 s[22:23], -1, 0
	s_cmpk_gt_i32 s3, 0x7f
	s_cselect_b64 s[2:3], -1, 0
	s_or_b64 s[64:65], s[22:23], s[2:3]
	s_mov_b64 s[22:23], -1
	s_and_b64 vcc, exec, s[64:65]
	s_cbranch_vccnz .LBB0_516
	v_lshl_add_u32 v142, s62, 8, v161
	v_add_u32_e32 v139, 4, v142
	v_add_u32_e32 v140, 8, v142
	v_add_u32_e32 v141, 12, v142
	v_add_u32_e32 v146, 0x4c, v142
	v_med3_i32 v138, v142, 0, v213
	v_med3_i32 v139, v139, 0, v213
	v_med3_i32 v140, v140, 0, v213
	v_med3_i32 v141, v141, 0, v213
	v_add_u32_e32 v143, 64, v142
	v_add_u32_e32 v144, 0x44, v142
	v_add_u32_e32 v145, 0x48, v142
	v_med3_i32 v146, v146, 0, v213
	v_add_u32_e32 v138, s27, v138
	v_add_u32_e32 v139, s27, v139
	v_add_u32_e32 v140, s27, v140
	v_add_u32_e32 v141, s27, v141
	v_med3_i32 v143, v143, 0, v213
	v_med3_i32 v144, v144, 0, v213
	v_med3_i32 v145, v145, 0, v213
	v_add_u32_e32 v150, s27, v146
	v_add_u32_e32 v143, s27, v143
	v_add_u32_e32 v144, s27, v144
	v_add_u32_e32 v145, s27, v145
	ds_read_b32 v146, v138
	ds_read_b32 v147, v139
	ds_read_b32 v148, v140
	ds_read_b32 v149, v141
	ds_read_b32 v138, v143
	ds_read_b32 v139, v144
	ds_read_b32 v140, v145
	ds_read_b32 v141, v150
	v_add_u32_e32 v150, 0x8c, v142
	v_med3_i32 v150, v150, 0, v213
	v_add_u32_e32 v153, s27, v150
	v_add_u32_e32 v150, 0xc0, v142
	v_med3_i32 v150, v150, 0, v213
	v_add_u32_e32 v216, s27, v150
	v_add_u32_e32 v150, 0xc4, v142
	v_add_u32_e32 v143, 0x80, v142
	v_add_u32_e32 v144, 0x84, v142
	v_add_u32_e32 v145, 0x88, v142
	v_med3_i32 v150, v150, 0, v213
	v_med3_i32 v143, v143, 0, v213
	v_med3_i32 v144, v144, 0, v213
	v_med3_i32 v145, v145, 0, v213
	v_add_u32_e32 v217, s27, v150
	v_add_u32_e32 v150, 0xc8, v142
	v_add_u32_e32 v142, 0xcc, v142
	v_add_u32_e32 v143, s27, v143
	v_add_u32_e32 v144, s27, v144
	v_add_u32_e32 v145, s27, v145
	v_med3_i32 v150, v150, 0, v213
	v_med3_i32 v142, v142, 0, v213
	v_add_u32_e32 v218, s27, v150
	v_add_u32_e32 v219, s27, v142
	ds_read_b32 v150, v143
	ds_read_b32 v151, v144
	ds_read_b32 v152, v145
	ds_read_b32 v153, v153
	ds_read_b32 v142, v216
	ds_read_b32 v143, v217
	ds_read_b32 v144, v218
	ds_read_b32 v145, v219
	s_mov_b64 s[22:23], 0

; #define AT_TR4(slot, d) do { const unsigned _a = vaddr + (unsigned)vo[d]; AT_TR(r[slot][0], _a, 0); AT_TR(r[slot][1], _a, 16 * 256); AT_TR(r[slot][2], _a, 32 * 256); AT_TR(r[slot][3], _a, 48 * 256); } while (0)
; #define AT_TR4(slot, d) do { const unsigned _a = vaddr + (unsigned)vo[d]; AT_TR(r[slot][0], _a, 0); AT_TR(r[slot][1], _a, 16 * 256); AT_TR(r[slot][2], _a, 32 * 256); AT_TR(r[slot][3], _a, 48 * 256); } while (0)
; template <bool QK, bool PV> ...
;     ...
;     if constexpr (PV) { AT_TR4(0, 0); AT_TR4(1, 1);
;         const bf16x8 ones = (bf16x8){0x3f80, 0x3f80, 0x3f80, 0x3f80, 0x3f80, 0x3f80, 0x3f80, 0x3f80};
; #pragma unroll
;         for (int c = 0; c < 2; ++c)
; #pragma unroll
;             for (int si = 0; si < 2; ++si) ol[c] = __builtin_amdgcn_mfma_f32_16x16x32_bf16(ones, pf[c][si], ol[c], 0, 0, 0); }
; #pragma unroll
;     for (int dt = 0; dt < 8; ++dt) {
;         if constexpr (PV) {
;             const int cb = dt % 3;
;             if (dt < 6) { AT_TR4((dt + 2) % 3, dt + 2); asm volatile("s_waitcnt lgkmcnt(8)" : "+v"(r[cb][0]), "+v"(r[cb][1]), "+v"(r[cb][2]), "+v"(r[cb][3])); }
;             else if (dt == 6) asm volatile("s_waitcnt lgkmcnt(4)" : "+v"(r[cb][0]), "+v"(r[cb][1]), "+v"(r[cb][2]), "+v"(r[cb][3]));
;             else asm volatile("s_waitcnt lgkmcnt(0)" : "+v"(r[cb][0]), "+v"(r[cb][1]), "+v"(r[cb][2]), "+v"(r[cb][3]));
; #pragma unroll
;             for (int si = 0; si < 2; ++si) {
;                 const s16x4 lo = r[cb][2 * si], hi = r[cb][2 * si + 1];
;                 const bf16x8 vf = (bf16x8){lo[0], lo[1], lo[2], lo[3], hi[0], hi[1], hi[2], hi[3]};
;                 o[0][dt] = __builtin_amdgcn_mfma_f32_16x16x32_bf16(vf, pf[0][si], o[0][dt], 0, 0, 0);
;                 o[1][dt] = __builtin_amdgcn_mfma_f32_16x16x32_bf16(vf, pf[1][si], o[1][dt], 0, 0, 0);
;             }
;         }
.LBB0_518:
	v_mov_b64_e32 v[218:219], s[6:7]
	v_mov_b64_e32 v[216:217], s[4:5]
	s_and_b32 s2, s55, 0xc000
	s_add_i32 s2, s2, 0
	s_add_i32 s2, s2, 0xc000
	v_mfma_f32_16x16x32_bf16 v[134:137], v[216:219], v[58:61], v[134:137]
	v_mfma_f32_16x16x32_bf16 v[130:133], v[216:219], v[42:45], v[130:133]
	v_mfma_f32_16x16x32_bf16 v[134:137], v[216:219], v[34:37], v[134:137]
	v_mfma_f32_16x16x32_bf16 v[130:133], v[216:219], v[18:21], v[130:133]
	v_add_u32_e32 v240, s2, v188
	ds_read_b64_tr_b16 v[216:217], v240 offset:0
	ds_read_b64_tr_b16 v[218:219], v240 offset:0x1000
	ds_read_b64_tr_b16 v[236:237], v240 offset:0x2000
	ds_read_b64_tr_b16 v[238:239], v240 offset:0x3000
	s_waitcnt lgkmcnt(8)
	v_add_u32_e32 v240, s2, v189
	v_mfma_f32_16x16x32_bf16 v[126:129], v[220:223], v[58:61], v[126:129]
	v_exp_f32_e32 v241, v28
	v_exp_f32_e32 v242, v29
	s_addk_i32 s55, 0x4000
	v_mfma_f32_16x16x32_bf16 v[122:125], v[220:223], v[42:45], v[122:125]
	ds_read_b64_tr_b16 v[220:221], v240 offset:0
	ds_read_b64_tr_b16 v[222:223], v240 offset:0x1000
	s_add_i32 s60, s60, 1
	v_mfma_f32_16x16x32_bf16 v[126:129], v[224:227], v[34:37], v[126:129]
	v_mfma_f32_16x16x32_bf16 v[122:125], v[224:227], v[18:21], v[122:125]
	ds_read_b64_tr_b16 v[224:225], v240 offset:0x2000
	ds_read_b64_tr_b16 v[226:227], v240 offset:0x3000
	s_waitcnt lgkmcnt(8)
	v_add_u32_e32 v240, s2, v190
	v_mfma_f32_16x16x32_bf16 v[114:117], v[228:231], v[58:61], v[114:117]
	v_mfma_f32_16x16x32_bf16 v[118:121], v[228:231], v[42:45], v[118:121]
	ds_read_b64_tr_b16 v[228:229], v240 offset:0
	ds_read_b64_tr_b16 v[230:231], v240 offset:0x1000
	v_mfma_f32_16x16x32_bf16 v[114:117], v[232:235], v[34:37], v[114:117]
	v_mfma_f32_16x16x32_bf16 v[118:121], v[232:235], v[18:21], v[118:121]
	ds_read_b64_tr_b16 v[232:233], v240 offset:0x2000
	ds_read_b64_tr_b16 v[234:235], v240 offset:0x3000
	s_waitcnt lgkmcnt(8)
	v_add_u32_e32 v240, s2, v191
	v_mfma_f32_16x16x32_bf16 v[106:109], v[216:219], v[58:61], v[106:109]
	v_mfma_f32_16x16x32_bf16 v[110:113], v[216:219], v[42:45], v[110:113]
	ds_read_b64_tr_b16 v[216:217], v240 offset:0
	ds_read_b64_tr_b16 v[218:219], v240 offset:0x1000
	v_mfma_f32_16x16x32_bf16 v[106:109], v[236:239], v[34:37], v[106:109]
	v_mfma_f32_16x16x32_bf16 v[110:113], v[236:239], v[18:21], v[110:113]
	ds_read_b64_tr_b16 v[236:237], v240 offset:0x2000
	ds_read_b64_tr_b16 v[238:239], v240 offset:0x3000
	s_waitcnt lgkmcnt(8)
	v_add_u32_e32 v240, s2, v192
	v_mfma_f32_16x16x32_bf16 v[98:101], v[220:223], v[58:61], v[98:101]
	v_mfma_f32_16x16x32_bf16 v[102:105], v[220:223], v[42:45], v[102:105]
	ds_read_b64_tr_b16 v[220:221], v240 offset:0
	ds_read_b64_tr_b16 v[222:223], v240 offset:0x1000
	v_mfma_f32_16x16x32_bf16 v[98:101], v[224:227], v[34:37], v[98:101]
	v_mfma_f32_16x16x32_bf16 v[102:105], v[224:227], v[18:21], v[102:105]
	ds_read_b64_tr_b16 v[224:225], v240 offset:0x2000
	ds_read_b64_tr_b16 v[226:227], v240 offset:0x3000
	s_waitcnt lgkmcnt(8)
	v_add_u32_e32 v240, s2, v193
	v_mfma_f32_16x16x32_bf16 v[78:81], v[228:231], v[58:61], v[78:81]
	s_add_i32 s2, s61, 0
	s_cmp_lg_u32 s54, s60
	v_mfma_f32_16x16x32_bf16 v[82:85], v[228:231], v[42:45], v[82:85]
	ds_read_b64_tr_b16 v[228:229], v240 offset:0
	ds_read_b64_tr_b16 v[230:231], v240 offset:0x1000
	v_mfma_f32_16x16x32_bf16 v[78:81], v[232:235], v[34:37], v[78:81]
	v_mfma_f32_16x16x32_bf16 v[82:85], v[232:235], v[18:21], v[82:85]
	ds_read_b64_tr_b16 v[232:233], v240 offset:0x2000
	ds_read_b64_tr_b16 v[234:235], v240 offset:0x3000
	s_waitcnt lgkmcnt(8)
	s_waitcnt lgkmcnt(4)
	v_exp_f32_e32 v240, v22
	v_mfma_f32_16x16x32_bf16 v[54:57], v[220:223], v[58:61], v[54:57]
	s_waitcnt lgkmcnt(0)
	s_barrier
; #define LAS __attribute__((address_space(3)))
; __device__ __forceinline__ unsigned cvtpk(float lo, float hi) { f32x2 v = {lo, hi}; bf16x2_t b = __builtin_convertvector(v, bf16x2_t); return __builtin_bit_cast(unsigned, b); }
; template <bool QK, bool PV> ...
;     ...
;     for (int dt = 0; dt < 8; ++dt) {
;         if constexpr (PV) {
;             const int cb = dt % 3;
;             if (dt < 6) { AT_TR4((dt + 2) % 3, dt + 2); asm volatile("s_waitcnt lgkmcnt(8)" : "+v"(r[cb][0]), "+v"(r[cb][1]), "+v"(r[cb][2]), "+v"(r[cb][3])); }
;             else if (dt == 6) asm volatile("s_waitcnt lgkmcnt(4)" : "+v"(r[cb][0]), "+v"(r[cb][1]), "+v"(r[cb][2]), "+v"(r[cb][3]));
;             else asm volatile("s_waitcnt lgkmcnt(0)" : "+v"(r[cb][0]), "+v"(r[cb][1]), "+v"(r[cb][2]), "+v"(r[cb][3]));
; #pragma unroll
;             for (int si = 0; si < 2; ++si) {
;                 const s16x4 lo = r[cb][2 * si], hi = r[cb][2 * si + 1];
;                 const bf16x8 vf = (bf16x8){lo[0], lo[1], lo[2], lo[3], hi[0], hi[1], hi[2], hi[3]};
;                 o[0][dt] = __builtin_amdgcn_mfma_f32_16x16x32_bf16(vf, pf[0][si], o[0][dt], 0, 0, 0);
;                 o[1][dt] = __builtin_amdgcn_mfma_f32_16x16x32_bf16(vf, pf[1][si], o[1][dt], 0, 0, 0);
;             }
;         }
;         {
;             const int c = dt >> 2, kt = dt & 3;
; #pragma unroll
;             for (int j = 0; j < 4; ++j) s[c][kt][j] = fast_exp2(s[c][kt][j]);
;             if (kt & 1) { const int si = kt >> 1;
;                 u32x4 wv; wv.x = cvtpk(s[c][2 * si][0], s[c][2 * si][1]); wv.y = cvtpk(s[c][2 * si][2], s[c][2 * si][3]);
;                 wv.z = cvtpk(s[c][2 * si + 1][0], s[c][2 * si + 1][1]); wv.w = cvtpk(s[c][2 * si + 1][2], s[c][2 * si + 1][3]);
;                 pn[c][si] = __builtin_bit_cast(bf16x8, wv); }
;         }
;     }
;     ...
; #pragma unroll
;     for (int c = 0; c < 2; ++c)
; #pragma unroll
;         for (int si = 0; si < 2; ++si) pf[c][si] = pn[c][si];
;     if constexpr (QK) {
; #pragma unroll
;         for (int kt = 0; kt < 4; ++kt)
; #pragma unroll
;             for (int c = 0; c < 2; ++c) {
;                 f32x4 a = tbv[kt];
; #pragma unroll
;                 for (int kk = 0; kk < 2; ++kk) { const bf16x8 kf = *(const LAS bf16x8*)(kbuf + kfo[c][kk] + kt * 4096); a = __builtin_amdgcn_mfma_f32_16x16x32_bf16(kf, qf[c][kk], a, 0, 0, 0); }
;                 s[c][kt] = a;
;             }
;     }
	s_add_i32 s99, s60, 3
	s_min_u32 s99, s99, s45
	s_add_i32 s99, s99, s46
	s_and_b32 s99, s99, s45
	s_lshl_b32 s99, s99, 16
	s_add_u32 s100, s47, s99
	s_addc_u32 s101, s48, 0
	s_add_i32 s99, s49, s59
	s_mov_b32 m0, s99
	s_nop 0
	global_load_lds_dwordx4 v154, s[100:101]
	s_add_i32 m0, s99, 0x400
	s_nop 0
	global_load_lds_dwordx4 v166, s[100:101]
	s_cmp_lg_u32 s54, s60
	v_mfma_f32_16x16x32_bf16 v[50:53], v[220:223], v[42:45], v[50:53]
	v_exp_f32_e32 v220, v88
	v_exp_f32_e32 v221, v89
	v_exp_f32_e32 v222, v90
	v_mfma_f32_16x16x32_bf16 v[54:57], v[224:227], v[34:37], v[54:57]
	v_exp_f32_e32 v223, v91
	v_mfma_f32_16x16x32_bf16 v[50:53], v[224:227], v[18:21], v[50:53]
	v_exp_f32_e32 v224, v94
	v_add_u32_e32 v94, s2, v182
	v_exp_f32_e32 v225, v95
	v_mfma_f32_16x16x32_bf16 v[66:69], v[216:219], v[58:61], v[66:69]
	v_exp_f32_e32 v226, v96
	v_exp_f32_e32 v95, v38
	v_exp_f32_e32 v96, v39
	v_mfma_f32_16x16x32_bf16 v[30:33], v[228:231], v[58:61], v[30:33]
	ds_read_b128 v[58:61], v94
	v_exp_f32_e32 v227, v97
	v_mfma_f32_16x16x32_bf16 v[70:73], v[216:219], v[42:45], v[70:73]
	v_exp_f32_e32 v216, v74
	v_exp_f32_e32 v217, v75
	v_exp_f32_e32 v218, v76
	v_mfma_f32_16x16x32_bf16 v[42:45], v[228:231], v[42:45], v[46:49]
	v_add_u32_e32 v230, s2, v183
	v_add_u32_e32 v231, s2, v184
	v_exp_f32_e32 v219, v77
	v_mfma_f32_16x16x32_bf16 v[66:69], v[236:239], v[34:37], v[66:69]
	v_exp_f32_e32 v228, v23
	v_exp_f32_e32 v229, v24
	v_mfma_f32_16x16x32_bf16 v[30:33], v[232:235], v[34:37], v[30:33]
	ds_read_b128 v[34:37], v230
	s_waitcnt lgkmcnt(1)
	v_mfma_f32_16x16x32_bf16 v[58:61], v[58:61], v[2:5], v[146:149]
	v_mfma_f32_16x16x32_bf16 v[70:73], v[236:239], v[18:21], v[70:73]
	v_exp_f32_e32 v236, v86
	v_exp_f32_e32 v237, v87
	v_exp_f32_e32 v238, v92
	v_mfma_f32_16x16x32_bf16 v[46:49], v[232:235], v[18:21], v[42:45]
	ds_read_b128 v[18:21], v231
	s_nop 1
	ds_read_b128 v[42:45], v94 offset:4096
	v_add_u32_e32 v232, s2, v185
	v_exp_f32_e32 v239, v93
	ds_read_b128 v[86:89], v232
	ds_read_b128 v[90:93], v230 offset:4096
	s_waitcnt lgkmcnt(4)
	v_mfma_f32_16x16x32_bf16 v[74:77], v[34:37], v[6:9], v[58:61]
	ds_read_b128 v[34:37], v231 offset:4096
	v_exp_f32_e32 v233, v25
	v_exp_f32_e32 v234, v26
	s_waitcnt lgkmcnt(4)
	v_mfma_f32_16x16x32_bf16 v[18:21], v[18:21], v[10:13], v[146:149]
	ds_read_b128 v[58:61], v232 offset:4096
	v_exp_f32_e32 v235, v27
	s_waitcnt lgkmcnt(3)
	v_mfma_f32_16x16x32_bf16 v[22:25], v[86:89], v[14:17], v[18:21]
	v_mfma_f32_16x16x32_bf16 v[18:21], v[42:45], v[2:5], v[138:141]
	v_exp_f32_e32 v42, v40
	v_exp_f32_e32 v43, v41
	ds_read_b128 v[38:41], v94 offset:8192
	s_waitcnt lgkmcnt(2)
	v_mfma_f32_16x16x32_bf16 v[26:29], v[34:37], v[10:13], v[138:141]
	ds_read_b128 v[34:37], v230 offset:8192
	v_exp_f32_e32 v44, v62
	v_exp_f32_e32 v45, v65
	v_mfma_f32_16x16x32_bf16 v[86:89], v[90:93], v[6:9], v[18:21]
	s_nop 2
	v_exp_f32_e32 v20, v63
	v_exp_f32_e32 v21, v64
	v_cvt_pk_bf16_f32 v18, v95, v96
	s_waitcnt lgkmcnt(2)
	v_mfma_f32_16x16x32_bf16 v[26:29], v[58:61], v[14:17], v[26:29]
	ds_read_b128 v[58:61], v231 offset:8192
	ds_read_b128 v[62:65], v94 offset:12288
	ds_read_b128 v[94:97], v232 offset:8192
	ds_read_b128 v[138:141], v230 offset:12288
	ds_read_b128 v[146:149], v231 offset:12288
	s_waitcnt lgkmcnt(6)
	v_mfma_f32_16x16x32_bf16 v[38:41], v[38:41], v[2:5], v[150:153]
	v_cvt_pk_bf16_f32 v19, v42, v43
	v_cvt_pk_bf16_f32 v20, v44, v20
	v_cvt_pk_bf16_f32 v21, v21, v45
	s_waitcnt lgkmcnt(5)
	v_mfma_f32_16x16x32_bf16 v[90:93], v[34:37], v[6:9], v[38:41]
	v_cvt_pk_bf16_f32 v42, v240, v228
	v_cvt_pk_bf16_f32 v43, v229, v233
	v_cvt_pk_bf16_f32 v44, v234, v235
	s_waitcnt lgkmcnt(4)
	v_mfma_f32_16x16x32_bf16 v[34:37], v[58:61], v[10:13], v[150:153]
	v_cvt_pk_bf16_f32 v45, v241, v242
	v_cvt_pk_bf16_f32 v58, v216, v217
	v_cvt_pk_bf16_f32 v59, v218, v219
	ds_read_b128 v[150:153], v232 offset:12288
	s_waitcnt lgkmcnt(4)
	v_mfma_f32_16x16x32_bf16 v[60:63], v[62:65], v[2:5], v[142:145]
	s_waitcnt vmcnt(4) lgkmcnt(0)
	s_barrier
	v_mfma_f32_16x16x32_bf16 v[38:41], v[94:97], v[14:17], v[34:37]
	v_mfma_f32_16x16x32_bf16 v[94:97], v[138:141], v[6:9], v[60:63]
	s_nop 1
	v_cvt_pk_bf16_f32 v34, v222, v223
	v_cvt_pk_bf16_f32 v35, v238, v239
	v_cvt_pk_bf16_f32 v36, v224, v225
	v_mfma_f32_16x16x32_bf16 v[62:65], v[146:149], v[10:13], v[142:145]
	v_cvt_pk_bf16_f32 v37, v226, v227
	v_cvt_pk_bf16_f32 v60, v236, v237
	v_cvt_pk_bf16_f32 v61, v220, v221
	v_mfma_f32_16x16x32_bf16 v[62:65], v[150:153], v[14:17], v[62:65]
	s_cbranch_scc0 .LBB0_502
	s_mov_b32 s2, s59
	s_mov_b32 s59, s61
	s_branch .LBB0_514

; #define LAS __attribute__((address_space(3)))
; #define AT_TR4(slot, d) do { const unsigned _a = vaddr + (unsigned)vo[d]; AT_TR(r[slot][0], _a, 0); AT_TR(r[slot][1], _a, 16 * 256); AT_TR(r[slot][2], _a, 32 * 256); AT_TR(r[slot][3], _a, 48 * 256); } while (0)
; #define AT_TR4(slot, d) do { const unsigned _a = vaddr + (unsigned)vo[d]; AT_TR(r[slot][0], _a, 0); AT_TR(r[slot][1], _a, 16 * 256); AT_TR(r[slot][2], _a, 32 * 256); AT_TR(r[slot][3], _a, 48 * 256); } while (0)
; template <bool QK, bool PV> ...
;     bf16x8 pn[2][2];
;     s16x4 r[3][4];
;     ...
;     if constexpr (PV) { AT_TR4(0, 0); AT_TR4(1, 1);
;         const bf16x8 ones = (bf16x8){0x3f80, 0x3f80, 0x3f80, 0x3f80, 0x3f80, 0x3f80, 0x3f80, 0x3f80};
; #pragma unroll
;         for (int c = 0; c < 2; ++c)
; #pragma unroll
;             for (int si = 0; si < 2; ++si) ol[c] = __builtin_amdgcn_mfma_f32_16x16x32_bf16(ones, pf[c][si], ol[c], 0, 0, 0); }
.Lat_xskip_p:
.LBB0_534:
	s_and_b32 s99, s53, 0xc000
	s_add_i32 s99, s99, 0xc000
	v_add_u32_e32 v217, s99, v175
	ds_read_b64_tr_b16 v[222:223], v217 offset:0
	ds_read_b64_tr_b16 v[224:225], v217 offset:0x1000
	ds_read_b64_tr_b16 v[226:227], v217 offset:0x2000
	ds_read_b64_tr_b16 v[228:229], v217 offset:0x3000
	v_add_u32_e32 v217, s99, v185
	ds_read_b64_tr_b16 v[230:231], v217 offset:0
	ds_read_b64_tr_b16 v[232:233], v217 offset:0x1000
	ds_read_b64_tr_b16 v[234:235], v217 offset:0x2000
	ds_read_b64_tr_b16 v[236:237], v217 offset:0x3000
	s_mov_b32 s3, s56
	s_add_i32 s56, s56, 1
	s_add_i32 s22, s3, 3
	s_min_u32 s22, s22, 31
	s_add_i32 s22, s22, s44
	s_lshl_b32 s22, s22, 16
	s_and_b32 s22, s22, 0x1f0000
	s_add_u32 s22, s20, s22
	s_addc_u32 s23, s48, 0
	s_add_i32 s57, s53, 0xffffc000
	s_and_b32 s57, s57, 0xc000
	s_add_i32 s57, s47, s57
	s_add_i32 m0, s57, 0xc000
	s_nop 0
	global_load_lds_dwordx4 v164, s[22:23]
	s_add_i32 m0, s57, 0xc400
	s_mov_b32 s57, s54
	global_load_lds_dwordx4 v168, s[22:23]
	s_mov_b32 s54, s2
	s_add_i32 s2, s50, s3
	s_and_b32 s58, s2, 31
	s_lshl_b32 s2, s58, 6
	s_sub_i32 s3, s2, s49
	s_cmp_lt_i32 s2, s51
	s_cselect_b64 s[22:23], -1, 0
	s_cmpk_gt_i32 s3, 0x7f
	s_cselect_b64 s[2:3], -1, 0
	s_or_b64 s[60:61], s[22:23], s[2:3]
	s_mov_b64 s[22:23], -1
	s_and_b64 vcc, exec, s[60:61]
	s_cbranch_vccnz .LBB0_536
	v_lshl_add_u32 v142, s58, 8, v214
	v_add_u32_e32 v139, 4, v142
	v_add_u32_e32 v140, 8, v142
	v_add_u32_e32 v141, 12, v142
	v_add_u32_e32 v146, 0x4c, v142
	v_med3_i32 v138, v142, 0, v213
	v_med3_i32 v139, v139, 0, v213
	v_med3_i32 v140, v140, 0, v213
	v_med3_i32 v141, v141, 0, v213
	v_add_u32_e32 v143, 64, v142
	v_add_u32_e32 v144, 0x44, v142
	v_add_u32_e32 v145, 0x48, v142
	v_med3_i32 v146, v146, 0, v213
	v_add_u32_e32 v138, s27, v138
	v_add_u32_e32 v139, s27, v139
	v_add_u32_e32 v140, s27, v140
	v_add_u32_e32 v141, s27, v141
	v_med3_i32 v143, v143, 0, v213
	v_med3_i32 v144, v144, 0, v213
	v_med3_i32 v145, v145, 0, v213
	v_add_u32_e32 v150, s27, v146
	v_add_u32_e32 v143, s27, v143
	v_add_u32_e32 v144, s27, v144
	v_add_u32_e32 v145, s27, v145
	ds_read_b32 v146, v138
	ds_read_b32 v147, v139
	ds_read_b32 v148, v140
	ds_read_b32 v149, v141
	ds_read_b32 v138, v143
	ds_read_b32 v139, v144
	ds_read_b32 v140, v145
	ds_read_b32 v141, v150
	v_add_u32_e32 v150, 0x8c, v142
	v_med3_i32 v150, v150, 0, v213
	v_add_u32_e32 v153, s27, v150
	v_add_u32_e32 v150, 0xc0, v142
	v_med3_i32 v150, v150, 0, v213
	v_add_u32_e32 v217, s27, v150
	v_add_u32_e32 v150, 0xc4, v142
	v_add_u32_e32 v143, 0x80, v142
	v_add_u32_e32 v144, 0x84, v142
	v_add_u32_e32 v145, 0x88, v142
	v_med3_i32 v150, v150, 0, v213
	v_med3_i32 v143, v143, 0, v213
	v_med3_i32 v144, v144, 0, v213
	v_med3_i32 v145, v145, 0, v213
	v_add_u32_e32 v218, s27, v150
	v_add_u32_e32 v150, 0xc8, v142
	v_add_u32_e32 v142, 0xcc, v142
	v_add_u32_e32 v143, s27, v143
	v_add_u32_e32 v144, s27, v144
	v_add_u32_e32 v145, s27, v145
	v_med3_i32 v150, v150, 0, v213
	v_med3_i32 v142, v142, 0, v213
	v_add_u32_e32 v219, s27, v150
	v_add_u32_e32 v220, s27, v142
	ds_read_b32 v150, v143
	ds_read_b32 v151, v144
	ds_read_b32 v152, v145
	ds_read_b32 v153, v153
	ds_read_b32 v142, v217
	ds_read_b32 v143, v218
	ds_read_b32 v144, v219
	ds_read_b32 v145, v220
	s_mov_b64 s[22:23], 0

; #define AT_TR4(slot, d) do { const unsigned _a = vaddr + (unsigned)vo[d]; AT_TR(r[slot][0], _a, 0); AT_TR(r[slot][1], _a, 16 * 256); AT_TR(r[slot][2], _a, 32 * 256); AT_TR(r[slot][3], _a, 48 * 256); } while (0)
; #define AT_TR4(slot, d) do { const unsigned _a = vaddr + (unsigned)vo[d]; AT_TR(r[slot][0], _a, 0); AT_TR(r[slot][1], _a, 16 * 256); AT_TR(r[slot][2], _a, 32 * 256); AT_TR(r[slot][3], _a, 48 * 256); } while (0)
; template <bool QK, bool PV> ...
;     ...
;     if constexpr (PV) { AT_TR4(0, 0); AT_TR4(1, 1);
;         const bf16x8 ones = (bf16x8){0x3f80, 0x3f80, 0x3f80, 0x3f80, 0x3f80, 0x3f80, 0x3f80, 0x3f80};
; #pragma unroll
;         for (int c = 0; c < 2; ++c)
; #pragma unroll
;             for (int si = 0; si < 2; ++si) ol[c] = __builtin_amdgcn_mfma_f32_16x16x32_bf16(ones, pf[c][si], ol[c], 0, 0, 0); }
; #pragma unroll
;     for (int dt = 0; dt < 8; ++dt) {
;         if constexpr (PV) {
;             const int cb = dt % 3;
;             if (dt < 6) { AT_TR4((dt + 2) % 3, dt + 2); asm volatile("s_waitcnt lgkmcnt(8)" : "+v"(r[cb][0]), "+v"(r[cb][1]), "+v"(r[cb][2]), "+v"(r[cb][3])); }
;             else if (dt == 6) asm volatile("s_waitcnt lgkmcnt(4)" : "+v"(r[cb][0]), "+v"(r[cb][1]), "+v"(r[cb][2]), "+v"(r[cb][3]));
;             else asm volatile("s_waitcnt lgkmcnt(0)" : "+v"(r[cb][0]), "+v"(r[cb][1]), "+v"(r[cb][2]), "+v"(r[cb][3]));
; #pragma unroll
;             for (int si = 0; si < 2; ++si) {
;                 const s16x4 lo = r[cb][2 * si], hi = r[cb][2 * si + 1];
;                 const bf16x8 vf = (bf16x8){lo[0], lo[1], lo[2], lo[3], hi[0], hi[1], hi[2], hi[3]};
;                 o[0][dt] = __builtin_amdgcn_mfma_f32_16x16x32_bf16(vf, pf[0][si], o[0][dt], 0, 0, 0);
;                 o[1][dt] = __builtin_amdgcn_mfma_f32_16x16x32_bf16(vf, pf[1][si], o[1][dt], 0, 0, 0);
;             }
;         }
.LBB0_538:
	v_mov_b64_e32 v[220:221], s[6:7]
	v_mov_b64_e32 v[218:219], s[4:5]
	s_and_b32 s2, s53, 0xc000
	s_add_i32 s2, s2, 0
	s_add_i32 s2, s2, 0xc000
	v_mfma_f32_16x16x32_bf16 v[134:137], v[218:221], v[58:61], v[134:137]
	v_mfma_f32_16x16x32_bf16 v[130:133], v[218:221], v[42:45], v[130:133]
	v_mfma_f32_16x16x32_bf16 v[134:137], v[218:221], v[34:37], v[134:137]
	v_mfma_f32_16x16x32_bf16 v[130:133], v[218:221], v[18:21], v[130:133]
	v_add_u32_e32 v217, s2, v186
	ds_read_b64_tr_b16 v[218:219], v217 offset:0
	ds_read_b64_tr_b16 v[220:221], v217 offset:0x1000
	ds_read_b64_tr_b16 v[238:239], v217 offset:0x2000
	ds_read_b64_tr_b16 v[240:241], v217 offset:0x3000
	s_waitcnt lgkmcnt(8)
	v_add_u32_e32 v217, s2, v187
	v_mfma_f32_16x16x32_bf16 v[126:129], v[222:225], v[58:61], v[126:129]
	v_exp_f32_e32 v242, v28
	v_exp_f32_e32 v243, v29
	s_addk_i32 s53, 0x4000
	v_mfma_f32_16x16x32_bf16 v[122:125], v[222:225], v[42:45], v[122:125]
	ds_read_b64_tr_b16 v[222:223], v217 offset:0
	ds_read_b64_tr_b16 v[224:225], v217 offset:0x1000
	v_mfma_f32_16x16x32_bf16 v[126:129], v[226:229], v[34:37], v[126:129]
	v_mfma_f32_16x16x32_bf16 v[122:125], v[226:229], v[18:21], v[122:125]
	ds_read_b64_tr_b16 v[226:227], v217 offset:0x2000
	ds_read_b64_tr_b16 v[228:229], v217 offset:0x3000
	s_waitcnt lgkmcnt(8)
	v_add_u32_e32 v217, s2, v188
	v_mfma_f32_16x16x32_bf16 v[114:117], v[230:233], v[58:61], v[114:117]
	v_mfma_f32_16x16x32_bf16 v[118:121], v[230:233], v[42:45], v[118:121]
	ds_read_b64_tr_b16 v[230:231], v217 offset:0
	ds_read_b64_tr_b16 v[232:233], v217 offset:0x1000
	v_mfma_f32_16x16x32_bf16 v[114:117], v[234:237], v[34:37], v[114:117]
	v_mfma_f32_16x16x32_bf16 v[118:121], v[234:237], v[18:21], v[118:121]
	ds_read_b64_tr_b16 v[234:235], v217 offset:0x2000
	ds_read_b64_tr_b16 v[236:237], v217 offset:0x3000
	s_waitcnt lgkmcnt(8)
	v_add_u32_e32 v217, s2, v189
	v_mfma_f32_16x16x32_bf16 v[106:109], v[218:221], v[58:61], v[106:109]
	v_mfma_f32_16x16x32_bf16 v[110:113], v[218:221], v[42:45], v[110:113]
	ds_read_b64_tr_b16 v[218:219], v217 offset:0
	ds_read_b64_tr_b16 v[220:221], v217 offset:0x1000
	v_mfma_f32_16x16x32_bf16 v[106:109], v[238:241], v[34:37], v[106:109]
	v_mfma_f32_16x16x32_bf16 v[110:113], v[238:241], v[18:21], v[110:113]
	ds_read_b64_tr_b16 v[238:239], v217 offset:0x2000
	ds_read_b64_tr_b16 v[240:241], v217 offset:0x3000
	s_waitcnt lgkmcnt(8)
	v_add_u32_e32 v217, s2, v190
	v_mfma_f32_16x16x32_bf16 v[98:101], v[222:225], v[58:61], v[98:101]
	v_mfma_f32_16x16x32_bf16 v[102:105], v[222:225], v[42:45], v[102:105]
	ds_read_b64_tr_b16 v[222:223], v217 offset:0
	ds_read_b64_tr_b16 v[224:225], v217 offset:0x1000
	v_mfma_f32_16x16x32_bf16 v[98:101], v[226:229], v[34:37], v[98:101]
	v_mfma_f32_16x16x32_bf16 v[102:105], v[226:229], v[18:21], v[102:105]
	ds_read_b64_tr_b16 v[226:227], v217 offset:0x2000
	ds_read_b64_tr_b16 v[228:229], v217 offset:0x3000
	s_waitcnt lgkmcnt(8)
	v_add_u32_e32 v217, s2, v191
	v_mfma_f32_16x16x32_bf16 v[78:81], v[230:233], v[58:61], v[78:81]
	s_add_i32 s2, s57, 0
	s_cmp_lg_u32 s56, 30
	v_mfma_f32_16x16x32_bf16 v[82:85], v[230:233], v[42:45], v[82:85]
	ds_read_b64_tr_b16 v[230:231], v217 offset:0
	ds_read_b64_tr_b16 v[232:233], v217 offset:0x1000
	v_mfma_f32_16x16x32_bf16 v[78:81], v[234:237], v[34:37], v[78:81]
	v_mfma_f32_16x16x32_bf16 v[82:85], v[234:237], v[18:21], v[82:85]
	ds_read_b64_tr_b16 v[234:235], v217 offset:0x2000
	ds_read_b64_tr_b16 v[236:237], v217 offset:0x3000
	s_waitcnt lgkmcnt(8)
	s_waitcnt lgkmcnt(4)
	v_exp_f32_e32 v217, v74
	v_mfma_f32_16x16x32_bf16 v[54:57], v[222:225], v[58:61], v[54:57]
	s_waitcnt lgkmcnt(0)
	s_barrier
; #define LAS __attribute__((address_space(3)))
; __device__ __forceinline__ unsigned cvtpk(float lo, float hi) { f32x2 v = {lo, hi}; bf16x2_t b = __builtin_convertvector(v, bf16x2_t); return __builtin_bit_cast(unsigned, b); }
; template <bool QK, bool PV> ...
;     ...
;     for (int dt = 0; dt < 8; ++dt) {
;         if constexpr (PV) {
;             const int cb = dt % 3;
;             if (dt < 6) { AT_TR4((dt + 2) % 3, dt + 2); asm volatile("s_waitcnt lgkmcnt(8)" : "+v"(r[cb][0]), "+v"(r[cb][1]), "+v"(r[cb][2]), "+v"(r[cb][3])); }
;             else if (dt == 6) asm volatile("s_waitcnt lgkmcnt(4)" : "+v"(r[cb][0]), "+v"(r[cb][1]), "+v"(r[cb][2]), "+v"(r[cb][3]));
;             else asm volatile("s_waitcnt lgkmcnt(0)" : "+v"(r[cb][0]), "+v"(r[cb][1]), "+v"(r[cb][2]), "+v"(r[cb][3]));
; #pragma unroll
;             for (int si = 0; si < 2; ++si) {
;                 const s16x4 lo = r[cb][2 * si], hi = r[cb][2 * si + 1];
;                 const bf16x8 vf = (bf16x8){lo[0], lo[1], lo[2], lo[3], hi[0], hi[1], hi[2], hi[3]};
;                 o[0][dt] = __builtin_amdgcn_mfma_f32_16x16x32_bf16(vf, pf[0][si], o[0][dt], 0, 0, 0);
;                 o[1][dt] = __builtin_amdgcn_mfma_f32_16x16x32_bf16(vf, pf[1][si], o[1][dt], 0, 0, 0);
;             }
;         }
;         {
;             const int c = dt >> 2, kt = dt & 3;
; #pragma unroll
;             for (int j = 0; j < 4; ++j) s[c][kt][j] = fast_exp2(s[c][kt][j]);
;             if (kt & 1) { const int si = kt >> 1;
;                 u32x4 wv; wv.x = cvtpk(s[c][2 * si][0], s[c][2 * si][1]); wv.y = cvtpk(s[c][2 * si][2], s[c][2 * si][3]);
;                 wv.z = cvtpk(s[c][2 * si + 1][0], s[c][2 * si + 1][1]); wv.w = cvtpk(s[c][2 * si + 1][2], s[c][2 * si + 1][3]);
;                 pn[c][si] = __builtin_bit_cast(bf16x8, wv); }
;         }
;     }
;     ...
; #pragma unroll
;     for (int c = 0; c < 2; ++c)
; #pragma unroll
;         for (int si = 0; si < 2; ++si) pf[c][si] = pn[c][si];
;     if constexpr (QK) {
; #pragma unroll
;         for (int kt = 0; kt < 4; ++kt)
; #pragma unroll
;             for (int c = 0; c < 2; ++c) {
;                 f32x4 a = tbv[kt];
; #pragma unroll
;                 for (int kk = 0; kk < 2; ++kk) { const bf16x8 kf = *(const LAS bf16x8*)(kbuf + kfo[c][kk] + kt * 4096); a = __builtin_amdgcn_mfma_f32_16x16x32_bf16(kf, qf[c][kk], a, 0, 0, 0); }
;                 s[c][kt] = a;
;             }
;     }
	s_min_u32 s99, s56, 28
	s_add_i32 s99, s52, s99
	s_lshl_b32 s99, s99, 16
	s_and_b32 s99, s99, 0x1f0000
	s_add_u32 s100, s45, s99
	s_addc_u32 s101, s46, 0
	s_add_i32 s99, s47, s55
	s_mov_b32 m0, s99
	s_nop 0
	global_load_lds_dwordx4 v154, s[100:101]
	s_add_i32 m0, s99, 0x400
	s_nop 0
	global_load_lds_dwordx4 v166, s[100:101]
	s_cmp_lg_u32 s56, 30
	v_mfma_f32_16x16x32_bf16 v[50:53], v[222:225], v[42:45], v[50:53]
	v_exp_f32_e32 v222, v88
	v_exp_f32_e32 v223, v89
	v_exp_f32_e32 v224, v90
	v_mfma_f32_16x16x32_bf16 v[54:57], v[226:229], v[34:37], v[54:57]
	v_exp_f32_e32 v225, v91
	v_mfma_f32_16x16x32_bf16 v[50:53], v[226:229], v[18:21], v[50:53]
	v_exp_f32_e32 v226, v94
	v_add_u32_e32 v94, s2, v176
	v_exp_f32_e32 v227, v95
	v_mfma_f32_16x16x32_bf16 v[66:69], v[218:221], v[58:61], v[66:69]
	v_exp_f32_e32 v228, v96
	v_exp_f32_e32 v95, v38
	v_exp_f32_e32 v96, v39
	v_mfma_f32_16x16x32_bf16 v[30:33], v[230:233], v[58:61], v[30:33]
	ds_read_b128 v[58:61], v94
	v_exp_f32_e32 v229, v97
	v_mfma_f32_16x16x32_bf16 v[70:73], v[218:221], v[42:45], v[70:73]
	v_exp_f32_e32 v218, v75
	v_exp_f32_e32 v219, v76
	v_exp_f32_e32 v220, v77
	v_mfma_f32_16x16x32_bf16 v[42:45], v[230:233], v[42:45], v[46:49]
	v_add_u32_e32 v232, s2, v182
	v_add_u32_e32 v233, s2, v183
	v_exp_f32_e32 v221, v86
	v_mfma_f32_16x16x32_bf16 v[66:69], v[238:241], v[34:37], v[66:69]
	v_exp_f32_e32 v230, v23
	v_exp_f32_e32 v231, v24
	v_mfma_f32_16x16x32_bf16 v[30:33], v[234:237], v[34:37], v[30:33]
	ds_read_b128 v[34:37], v232
	s_waitcnt lgkmcnt(1)
	v_mfma_f32_16x16x32_bf16 v[58:61], v[58:61], v[2:5], v[146:149]
	v_mfma_f32_16x16x32_bf16 v[70:73], v[238:241], v[18:21], v[70:73]
	v_exp_f32_e32 v238, v87
	v_exp_f32_e32 v239, v92
	v_exp_f32_e32 v240, v93
	v_mfma_f32_16x16x32_bf16 v[46:49], v[234:237], v[18:21], v[42:45]
	ds_read_b128 v[18:21], v233
	s_nop 1
	ds_read_b128 v[42:45], v94 offset:4096
	v_add_u32_e32 v234, s2, v184
	ds_read_b128 v[86:89], v234
	ds_read_b128 v[90:93], v232 offset:4096
	s_waitcnt lgkmcnt(4)
	v_mfma_f32_16x16x32_bf16 v[74:77], v[34:37], v[6:9], v[58:61]
	ds_read_b128 v[34:37], v233 offset:4096
	v_exp_f32_e32 v241, v22
	v_exp_f32_e32 v235, v25
	s_waitcnt lgkmcnt(4)
	v_mfma_f32_16x16x32_bf16 v[18:21], v[18:21], v[10:13], v[146:149]
	ds_read_b128 v[58:61], v234 offset:4096
	v_exp_f32_e32 v236, v26
	v_exp_f32_e32 v237, v27
	s_waitcnt lgkmcnt(3)
	v_mfma_f32_16x16x32_bf16 v[22:25], v[86:89], v[14:17], v[18:21]
	v_mfma_f32_16x16x32_bf16 v[18:21], v[42:45], v[2:5], v[138:141]
	v_exp_f32_e32 v42, v40
	v_exp_f32_e32 v43, v41
	ds_read_b128 v[38:41], v94 offset:8192
	s_waitcnt lgkmcnt(2)
	v_mfma_f32_16x16x32_bf16 v[26:29], v[34:37], v[10:13], v[138:141]
	ds_read_b128 v[34:37], v232 offset:8192
	v_exp_f32_e32 v44, v62
	v_exp_f32_e32 v45, v65
	v_mfma_f32_16x16x32_bf16 v[86:89], v[90:93], v[6:9], v[18:21]
	s_nop 2
	v_exp_f32_e32 v20, v63
	v_exp_f32_e32 v21, v64
	v_cvt_pk_bf16_f32 v18, v95, v96
	s_waitcnt lgkmcnt(2)
	v_mfma_f32_16x16x32_bf16 v[26:29], v[58:61], v[14:17], v[26:29]
	ds_read_b128 v[58:61], v233 offset:8192
	ds_read_b128 v[62:65], v94 offset:12288
	ds_read_b128 v[94:97], v234 offset:8192
	ds_read_b128 v[138:141], v232 offset:12288
	ds_read_b128 v[146:149], v233 offset:12288
	s_waitcnt lgkmcnt(6)
	v_mfma_f32_16x16x32_bf16 v[38:41], v[38:41], v[2:5], v[150:153]
	v_cvt_pk_bf16_f32 v19, v42, v43
	v_cvt_pk_bf16_f32 v20, v44, v20
	v_cvt_pk_bf16_f32 v21, v21, v45
	s_waitcnt lgkmcnt(5)
	v_mfma_f32_16x16x32_bf16 v[90:93], v[34:37], v[6:9], v[38:41]
	v_cvt_pk_bf16_f32 v42, v241, v230
	v_cvt_pk_bf16_f32 v43, v231, v235
	v_cvt_pk_bf16_f32 v44, v236, v237
	s_waitcnt lgkmcnt(4)
	v_mfma_f32_16x16x32_bf16 v[34:37], v[58:61], v[10:13], v[150:153]
	v_cvt_pk_bf16_f32 v45, v242, v243
	v_cvt_pk_bf16_f32 v58, v217, v218
	v_cvt_pk_bf16_f32 v59, v219, v220
	ds_read_b128 v[150:153], v234 offset:12288
	s_waitcnt lgkmcnt(4)
	v_mfma_f32_16x16x32_bf16 v[60:63], v[62:65], v[2:5], v[142:145]
	s_waitcnt vmcnt(4) lgkmcnt(0)
	s_barrier
	v_mfma_f32_16x16x32_bf16 v[38:41], v[94:97], v[14:17], v[34:37]
	v_mfma_f32_16x16x32_bf16 v[94:97], v[138:141], v[6:9], v[60:63]
	s_nop 1
	v_cvt_pk_bf16_f32 v34, v224, v225
	v_cvt_pk_bf16_f32 v35, v239, v240
	v_cvt_pk_bf16_f32 v36, v226, v227
	v_mfma_f32_16x16x32_bf16 v[62:65], v[146:149], v[10:13], v[142:145]
	v_cvt_pk_bf16_f32 v37, v228, v229
	v_cvt_pk_bf16_f32 v60, v221, v238
	v_cvt_pk_bf16_f32 v61, v222, v223
	v_mfma_f32_16x16x32_bf16 v[62:65], v[150:153], v[14:17], v[62:65]
	s_cbranch_scc0 .LBB0_522
	s_mov_b32 s2, s55
	s_mov_b32 s55, s57
	s_branch .LBB0_534
